# w_gate conversion moved from the early pass (before SEAM 1) into the overlapped late pass (first read after SEAM 3)
# speedup vs baseline: 1.0070x; 1.0070x over previous
.LBB0_19:
	s_mov_b32 s98, 0
	s_sub_u32 s100, s45, 0x6400
	s_cmpk_lt_u32 s100, 0x100
	s_cselect_b32 s98, 1, s98
	s_sub_u32 s100, s45, 0xad00
	s_cmpk_lt_u32 s100, 0x100
	s_cselect_b32 s98, 1, s98
	s_cmp_lg_u32 s98, s99
	s_cbranch_scc1 .LBB0_18
	s_cmpk_gt_i32 s45, 0x7ff
	s_mov_b64 s[6:7], -1
	s_cbranch_scc0 .LBB0_181
	s_cmpk_gt_u32 s45, 0xfff
	s_cbranch_scc0 .LBB0_176
	s_waitcnt lgkmcnt(0)
	s_load_dwordx4 s[8:11], s[18:19], 0x100
	s_cmpk_gt_u32 s45, 0x11ff
	s_cbranch_scc0 .LBB0_149
	s_cmpk_gt_u32 s45, 0x13ff
	s_cbranch_scc0 .LBB0_122
	s_cmpk_gt_u32 s45, 0x1bff
	s_cbranch_scc0 .LBB0_95
	s_add_i32 s46, s45, 0xffffe400
	s_cmpk_gt_u32 s46, 0x7ff
	s_cbranch_scc0 .LBB0_90
	s_add_i32 s28, s45, 0xffffdc00
	s_cmpk_gt_u32 s28, 0x48ff
	s_cselect_b64 s[22:23], -1, 0
	s_and_b64 s[6:7], s[22:23], exec
	s_cselect_b32 s20, 0xffffb700, 0
	s_add_i32 s29, s20, s28
	s_cmpk_gt_i32 s29, 0x1fff
	s_mov_b64 s[6:7], -1
	s_cbranch_scc0 .LBB0_63
	s_cmpk_gt_u32 s29, 0x3fff
	s_cbranch_scc0 .LBB0_58
	s_cmpk_gt_u32 s29, 0x40ff
	s_cbranch_scc0 .LBB0_53
	s_mov_b64 s[6:7], 0
	s_branch .LBB0_53
	s_load_dwordx4 s[12:15], s[18:19], 0xe0
	s_load_dwordx2 s[24:25], s[18:19], 0xf8
	s_and_b64 s[26:27], s[22:23], exec
	s_cselect_b32 s49, 0x800, 0
	s_lshl_b32 s7, s49, 13
	v_mov_b32_e32 v33, v5
	s_waitcnt lgkmcnt(0)
	s_add_u32 s7, s24, s7
	s_addc_u32 s25, s25, 0
	s_add_i32 s24, s29, 0xbf00
	s_and_b32 s48, s24, 0xffc0
	s_lshl_b32 s24, s45, 5
	s_and_b32 s47, s24, 0x7e0
	s_lshl_b32 s24, s47, 2
	s_add_u32 s24, s7, s24
	s_addc_u32 s25, s25, 0
	s_mov_b32 s6, 0
	v_lshl_add_u64 v[34:35], s[24:25], 0, v[32:33]
	s_mov_b32 s7, s48
	s_mov_b32 s24, 1
	s_mov_b32 s25, 32
